# write-through only on 16-byte stores; 8-byte stores back to default policy
# speedup vs baseline: 1.0049x; 1.0049x over previous
.LBB0_2011:
	v_mov_b32_e32 v154, 0
	v_mov_b32_e32 v155, 0
	v_cvt_pk_fp8_f32 v154, v144, v145
	v_cvt_pk_fp8_f32 v155, v150, v151
	v_lshlrev_b64 v[152:153], 6, v[152:153]
	v_lshl_add_u64 v[152:153], v[180:181], 0, v[152:153]
	v_cvt_pk_fp8_f32 v154, v146, v147 op_sel:[0,0,1]
	v_cvt_pk_fp8_f32 v155, v148, v149 op_sel:[0,0,1]
	v_subrev_u32_e32 v152, s38, v152
	v_lshrrev_b32_e32 v252, 2, v152
	v_lshlrev_b32_e32 v253, 4, v152
	v_and_b32_e32 v252, 0xf0, v252
	v_and_b32_e32 v253, 0x300, v253
	v_and_b32_e32 v152, 0xfffffc0f, v152
	v_or3_b32 v152, v152, v252, v253
	v_add_u32_e32 v152, s38, v152
	global_store_dwordx2 v[152:153], v[154:155], off

.LBB0_2036:
	v_mov_b32_e32 v130, v171
	v_mov_b32_e32 v131, v171
	v_cvt_pk_fp8_f32 v130, v124, v125
	v_cvt_pk_fp8_f32 v131, v120, v121
	v_lshlrev_b64 v[128:129], 6, v[128:129]
	v_lshl_add_u64 v[128:129], v[184:185], 0, v[128:129]
	v_cvt_pk_fp8_f32 v130, v126, v127 op_sel:[0,0,1]
	v_cvt_pk_fp8_f32 v131, v122, v123 op_sel:[0,0,1]
	v_subrev_u32_e32 v128, s38, v128
	v_lshrrev_b32_e32 v252, 2, v128
	v_lshlrev_b32_e32 v253, 4, v128
	v_and_b32_e32 v252, 0xf0, v252
	v_and_b32_e32 v253, 0x300, v253
	v_and_b32_e32 v128, 0xfffffc0f, v128
	v_or3_b32 v128, v128, v252, v253
	v_add_u32_e32 v128, s38, v128
	global_store_dwordx2 v[128:129], v[130:131], off

.LBB0_2058:
	v_mov_b32_e32 v146, v171
	v_mov_b32_e32 v147, v171
	v_cvt_pk_fp8_f32 v146, v136, v137
	v_cvt_pk_fp8_f32 v147, v142, v143
	v_lshlrev_b64 v[144:145], 6, v[144:145]
	v_lshl_add_u64 v[144:145], v[180:181], 0, v[144:145]
	v_cvt_pk_fp8_f32 v146, v138, v139 op_sel:[0,0,1]
	v_cvt_pk_fp8_f32 v147, v140, v141 op_sel:[0,0,1]
	v_subrev_u32_e32 v144, s38, v144
	v_lshrrev_b32_e32 v252, 2, v144
	v_lshlrev_b32_e32 v253, 4, v144
	v_and_b32_e32 v252, 0xf0, v252
	v_and_b32_e32 v253, 0x300, v253
	v_and_b32_e32 v144, 0xfffffc0f, v144
	v_or3_b32 v144, v144, v252, v253
	v_add_u32_e32 v144, s38, v144
	global_store_dwordx2 v[144:145], v[146:147], off

.LBB0_2083:
	v_mov_b32_e32 v122, v171
	v_mov_b32_e32 v123, v171
	v_cvt_pk_fp8_f32 v122, v116, v117
	v_cvt_pk_fp8_f32 v123, v112, v113
	v_lshlrev_b64 v[120:121], 6, v[120:121]
	v_lshl_add_u64 v[120:121], v[184:185], 0, v[120:121]
	v_cvt_pk_fp8_f32 v122, v118, v119 op_sel:[0,0,1]
	v_cvt_pk_fp8_f32 v123, v114, v115 op_sel:[0,0,1]
	v_subrev_u32_e32 v120, s38, v120
	v_lshrrev_b32_e32 v252, 2, v120
	v_lshlrev_b32_e32 v253, 4, v120
	v_and_b32_e32 v252, 0xf0, v252
	v_and_b32_e32 v253, 0x300, v253
	v_and_b32_e32 v120, 0xfffffc0f, v120
	v_or3_b32 v120, v120, v252, v253
	v_add_u32_e32 v120, s38, v120
	global_store_dwordx2 v[120:121], v[122:123], off

.LBB0_2105:
	v_mov_b32_e32 v138, v171
	v_mov_b32_e32 v139, v171
	v_cvt_pk_fp8_f32 v138, v128, v129
	v_cvt_pk_fp8_f32 v139, v134, v135
	v_lshlrev_b64 v[136:137], 6, v[136:137]
	v_lshl_add_u64 v[136:137], v[180:181], 0, v[136:137]
	v_cvt_pk_fp8_f32 v138, v130, v131 op_sel:[0,0,1]
	v_cvt_pk_fp8_f32 v139, v132, v133 op_sel:[0,0,1]
	v_subrev_u32_e32 v136, s38, v136
	v_lshrrev_b32_e32 v252, 2, v136
	v_lshlrev_b32_e32 v253, 4, v136
	v_and_b32_e32 v252, 0xf0, v252
	v_and_b32_e32 v253, 0x300, v253
	v_and_b32_e32 v136, 0xfffffc0f, v136
	v_or3_b32 v136, v136, v252, v253
	v_add_u32_e32 v136, s38, v136
	global_store_dwordx2 v[136:137], v[138:139], off

.LBB0_2130:
	v_mov_b32_e32 v114, v171
	v_mov_b32_e32 v115, v171
	v_cvt_pk_fp8_f32 v114, v108, v109
	v_cvt_pk_fp8_f32 v115, v104, v105
	v_lshlrev_b64 v[112:113], 6, v[112:113]
	v_lshl_add_u64 v[112:113], v[184:185], 0, v[112:113]
	v_cvt_pk_fp8_f32 v114, v110, v111 op_sel:[0,0,1]
	v_cvt_pk_fp8_f32 v115, v106, v107 op_sel:[0,0,1]
	v_subrev_u32_e32 v112, s38, v112
	v_lshrrev_b32_e32 v252, 2, v112
	v_lshlrev_b32_e32 v253, 4, v112
	v_and_b32_e32 v252, 0xf0, v252
	v_and_b32_e32 v253, 0x300, v253
	v_and_b32_e32 v112, 0xfffffc0f, v112
	v_or3_b32 v112, v112, v252, v253
	v_add_u32_e32 v112, s38, v112
	global_store_dwordx2 v[112:113], v[114:115], off

.LBB0_2152:
	v_mov_b32_e32 v130, v171
	v_mov_b32_e32 v131, v171
	v_cvt_pk_fp8_f32 v130, v120, v121
	v_cvt_pk_fp8_f32 v131, v126, v127
	v_lshlrev_b64 v[128:129], 6, v[128:129]
	v_lshl_add_u64 v[128:129], v[180:181], 0, v[128:129]
	v_cvt_pk_fp8_f32 v130, v122, v123 op_sel:[0,0,1]
	v_cvt_pk_fp8_f32 v131, v124, v125 op_sel:[0,0,1]
	v_subrev_u32_e32 v128, s38, v128
	v_lshrrev_b32_e32 v252, 2, v128
	v_lshlrev_b32_e32 v253, 4, v128
	v_and_b32_e32 v252, 0xf0, v252
	v_and_b32_e32 v253, 0x300, v253
	v_and_b32_e32 v128, 0xfffffc0f, v128
	v_or3_b32 v128, v128, v252, v253
	v_add_u32_e32 v128, s38, v128
	global_store_dwordx2 v[128:129], v[130:131], off

.LBB0_2177:
	v_mov_b32_e32 v106, v171
	v_mov_b32_e32 v107, v171
	v_cvt_pk_fp8_f32 v106, v100, v101
	v_cvt_pk_fp8_f32 v107, v96, v97
	v_lshlrev_b64 v[104:105], 6, v[104:105]
	v_lshl_add_u64 v[104:105], v[184:185], 0, v[104:105]
	v_cvt_pk_fp8_f32 v106, v102, v103 op_sel:[0,0,1]
	v_cvt_pk_fp8_f32 v107, v98, v99 op_sel:[0,0,1]
	v_subrev_u32_e32 v104, s38, v104
	v_lshrrev_b32_e32 v252, 2, v104
	v_lshlrev_b32_e32 v253, 4, v104
	v_and_b32_e32 v252, 0xf0, v252
	v_and_b32_e32 v253, 0x300, v253
	v_and_b32_e32 v104, 0xfffffc0f, v104
	v_or3_b32 v104, v104, v252, v253
	v_add_u32_e32 v104, s38, v104
	global_store_dwordx2 v[104:105], v[106:107], off

.LBB0_2199:
	v_mov_b32_e32 v122, v171
	v_mov_b32_e32 v123, v171
	v_cvt_pk_fp8_f32 v122, v112, v113
	v_cvt_pk_fp8_f32 v123, v118, v119
	v_lshlrev_b64 v[120:121], 6, v[120:121]
	v_lshl_add_u64 v[120:121], v[180:181], 0, v[120:121]
	v_cvt_pk_fp8_f32 v122, v114, v115 op_sel:[0,0,1]
	v_cvt_pk_fp8_f32 v123, v116, v117 op_sel:[0,0,1]
	v_subrev_u32_e32 v120, s38, v120
	v_lshrrev_b32_e32 v252, 2, v120
	v_lshlrev_b32_e32 v253, 4, v120
	v_and_b32_e32 v252, 0xf0, v252
	v_and_b32_e32 v253, 0x300, v253
	v_and_b32_e32 v120, 0xfffffc0f, v120
	v_or3_b32 v120, v120, v252, v253
	v_add_u32_e32 v120, s38, v120
	global_store_dwordx2 v[120:121], v[122:123], off

.LBB0_2224:
	v_mov_b32_e32 v98, v171
	v_mov_b32_e32 v99, v171
	v_cvt_pk_fp8_f32 v98, v92, v93
	v_cvt_pk_fp8_f32 v99, v88, v89
	v_lshlrev_b64 v[96:97], 6, v[96:97]
	v_lshl_add_u64 v[96:97], v[184:185], 0, v[96:97]
	v_cvt_pk_fp8_f32 v98, v94, v95 op_sel:[0,0,1]
	v_cvt_pk_fp8_f32 v99, v90, v91 op_sel:[0,0,1]
	v_subrev_u32_e32 v96, s38, v96
	v_lshrrev_b32_e32 v252, 2, v96
	v_lshlrev_b32_e32 v253, 4, v96
	v_and_b32_e32 v252, 0xf0, v252
	v_and_b32_e32 v253, 0x300, v253
	v_and_b32_e32 v96, 0xfffffc0f, v96
	v_or3_b32 v96, v96, v252, v253
	v_add_u32_e32 v96, s38, v96
	global_store_dwordx2 v[96:97], v[98:99], off

.LBB0_2246:
	v_mov_b32_e32 v114, v171
	v_mov_b32_e32 v115, v171
	v_cvt_pk_fp8_f32 v114, v104, v105
	v_cvt_pk_fp8_f32 v115, v110, v111
	v_lshlrev_b64 v[112:113], 6, v[112:113]
	v_lshl_add_u64 v[112:113], v[180:181], 0, v[112:113]
	v_cvt_pk_fp8_f32 v114, v106, v107 op_sel:[0,0,1]
	v_cvt_pk_fp8_f32 v115, v108, v109 op_sel:[0,0,1]
	v_subrev_u32_e32 v112, s38, v112
	v_lshrrev_b32_e32 v252, 2, v112
	v_lshlrev_b32_e32 v253, 4, v112
	v_and_b32_e32 v252, 0xf0, v252
	v_and_b32_e32 v253, 0x300, v253
	v_and_b32_e32 v112, 0xfffffc0f, v112
	v_or3_b32 v112, v112, v252, v253
	v_add_u32_e32 v112, s38, v112
	global_store_dwordx2 v[112:113], v[114:115], off

.LBB0_2271:
	v_mov_b32_e32 v90, v171
	v_mov_b32_e32 v91, v171
	v_cvt_pk_fp8_f32 v90, v84, v85
	v_cvt_pk_fp8_f32 v91, v80, v81
	v_lshlrev_b64 v[88:89], 6, v[88:89]
	v_lshl_add_u64 v[88:89], v[184:185], 0, v[88:89]
	v_cvt_pk_fp8_f32 v90, v86, v87 op_sel:[0,0,1]
	v_cvt_pk_fp8_f32 v91, v82, v83 op_sel:[0,0,1]
	v_subrev_u32_e32 v88, s38, v88
	v_lshrrev_b32_e32 v252, 2, v88
	v_lshlrev_b32_e32 v253, 4, v88
	v_and_b32_e32 v252, 0xf0, v252
	v_and_b32_e32 v253, 0x300, v253
	v_and_b32_e32 v88, 0xfffffc0f, v88
	v_or3_b32 v88, v88, v252, v253
	v_add_u32_e32 v88, s38, v88
	global_store_dwordx2 v[88:89], v[90:91], off

.LBB0_2293:
	v_mov_b32_e32 v106, v171
	v_mov_b32_e32 v107, v171
	v_cvt_pk_fp8_f32 v106, v96, v97
	v_cvt_pk_fp8_f32 v107, v102, v103
	v_lshlrev_b64 v[104:105], 6, v[104:105]
	v_lshl_add_u64 v[104:105], v[180:181], 0, v[104:105]
	v_cvt_pk_fp8_f32 v106, v98, v99 op_sel:[0,0,1]
	v_cvt_pk_fp8_f32 v107, v100, v101 op_sel:[0,0,1]
	v_subrev_u32_e32 v104, s38, v104
	v_lshrrev_b32_e32 v252, 2, v104
	v_lshlrev_b32_e32 v253, 4, v104
	v_and_b32_e32 v252, 0xf0, v252
	v_and_b32_e32 v253, 0x300, v253
	v_and_b32_e32 v104, 0xfffffc0f, v104
	v_or3_b32 v104, v104, v252, v253
	v_add_u32_e32 v104, s38, v104
	global_store_dwordx2 v[104:105], v[106:107], off

.LBB0_2318:
	v_mov_b32_e32 v82, v171
	v_mov_b32_e32 v83, v171
	v_cvt_pk_fp8_f32 v82, v76, v77
	v_cvt_pk_fp8_f32 v83, v72, v73
	v_lshlrev_b64 v[80:81], 6, v[80:81]
	v_lshl_add_u64 v[80:81], v[184:185], 0, v[80:81]
	v_cvt_pk_fp8_f32 v82, v78, v79 op_sel:[0,0,1]
	v_cvt_pk_fp8_f32 v83, v74, v75 op_sel:[0,0,1]
	v_subrev_u32_e32 v80, s38, v80
	v_lshrrev_b32_e32 v252, 2, v80
	v_lshlrev_b32_e32 v253, 4, v80
	v_and_b32_e32 v252, 0xf0, v252
	v_and_b32_e32 v253, 0x300, v253
	v_and_b32_e32 v80, 0xfffffc0f, v80
	v_or3_b32 v80, v80, v252, v253
	v_add_u32_e32 v80, s38, v80
	global_store_dwordx2 v[80:81], v[82:83], off

.LBB0_2340:
	v_mov_b32_e32 v98, v171
	v_mov_b32_e32 v99, v171
	v_cvt_pk_fp8_f32 v98, v88, v89
	v_cvt_pk_fp8_f32 v99, v94, v95
	v_lshlrev_b64 v[96:97], 6, v[96:97]
	v_lshl_add_u64 v[96:97], v[180:181], 0, v[96:97]
	v_cvt_pk_fp8_f32 v98, v90, v91 op_sel:[0,0,1]
	v_cvt_pk_fp8_f32 v99, v92, v93 op_sel:[0,0,1]
	v_subrev_u32_e32 v96, s38, v96
	v_lshrrev_b32_e32 v252, 2, v96
	v_lshlrev_b32_e32 v253, 4, v96
	v_and_b32_e32 v252, 0xf0, v252
	v_and_b32_e32 v253, 0x300, v253
	v_and_b32_e32 v96, 0xfffffc0f, v96
	v_or3_b32 v96, v96, v252, v253
	v_add_u32_e32 v96, s38, v96
	global_store_dwordx2 v[96:97], v[98:99], off

.LBB0_2362:
	v_mov_b32_e32 v74, v171
	v_mov_b32_e32 v75, v171
	v_cvt_pk_fp8_f32 v74, v68, v69
	v_cvt_pk_fp8_f32 v75, v64, v65
	v_lshlrev_b64 v[72:73], 6, v[72:73]
	v_lshl_add_u64 v[72:73], v[184:185], 0, v[72:73]
	v_cvt_pk_fp8_f32 v74, v70, v71 op_sel:[0,0,1]
	v_cvt_pk_fp8_f32 v75, v66, v67 op_sel:[0,0,1]
	v_subrev_u32_e32 v72, s38, v72
	v_lshrrev_b32_e32 v252, 2, v72
	v_lshlrev_b32_e32 v253, 4, v72
	v_and_b32_e32 v252, 0xf0, v252
	v_and_b32_e32 v253, 0x300, v253
	v_and_b32_e32 v72, 0xfffffc0f, v72
	v_or3_b32 v72, v72, v252, v253
	v_add_u32_e32 v72, s38, v72
	global_store_dwordx2 v[72:73], v[74:75], off
